# GEMM K-loops: one s_setprio 1 window per super-phase (mid-segment s_setprio 0/1 pair removed)
# speedup vs baseline: 1.0078x; 1.0050x over previous
; #define PG8_STAGE(bufoff, gbase, voff) do { _Pragma("unroll") for (int _i = 0; _i < 2; ++_i) \
;         __builtin_amdgcn_global_load_lds((const unsigned*)((const char*)(gbase) + (voff)[_i]), (PG8_LAS unsigned*)(lds + (bufoff) + ldsw + _i * 8192), 16, 0, 0); } while (0)
; #define PG8_LDA(dst, b, h) do { _Pragma("unroll") for (int m = 0; m < 4; ++m) _Pragma("unroll") for (int k = 0; k < 2; ++k) dst[m][k] = *(const PG8_LAS bf16x8*)(lds + PG8_SA(b, h) + aoff + m * 2048 + k * 1024); } while (0)
; #define PG8_LDB(dst, b, h) do { _Pragma("unroll") for (int n = 0; n < 2; ++n) _Pragma("unroll") for (int k = 0; k < 2; ++k) dst[n][k] = *(const PG8_LAS bf16x8*)(lds + PG8_SB(b, h) + boff + n * 2048 + k * 1024); } while (0)
; #define PG8_MMA(ai, bj, At, Bt) do { __builtin_amdgcn_s_setprio(1); _Pragma("unroll") for (int m = 0; m < 4; ++m) _Pragma("unroll") for (int n = 0; n < 2; ++n) _Pragma("unroll") for (int k = 0; k < 2; ++k) \
;         acc[ai][bj][m][n] = __builtin_amdgcn_mfma_f32_16x16x32_bf16(Bt[n][k], At[m][k], acc[ai][bj][m][n], 0, 0, 0); __builtin_amdgcn_s_setprio(0); } while (0)
; #define PG8_WAIT_V(n) asm volatile("s_waitcnt vmcnt(" #n ")" ::: "memory")
; #define PG8_WAIT_L(n) asm volatile("s_waitcnt lgkmcnt(" #n ")" ::: "memory")
; #define PG8_BAR __builtin_amdgcn_s_barrier()
; #define PG8_SCHED __builtin_amdgcn_sched_barrier(0)
; template <class Epi, class Sched, bool ALIGN_EPI = false, bool SP2 = false>
; __device__ __forceinline__ void gemm_phase(PG8_LAS unsigned char* lds, const Gemm g, const Sched& S, const Epi& E, int tid_in) {
;     ...
;             PG8_LDB(B0, 0, 0); PG8_LDB(B1, 0, 1); PG8_SCHED; PG8_LDA(At, 0, 0); PG8_STAGE(PG8_SA(1, 1), a1 + hstep, voffA);
;             PG8_WAIT_V(8); PG8_WAIT_L(0); PG8_BAR; PG8_MMA(0, 0, At, B0); PG8_MMA(0, 1, At, B1); PG8_BAR; PG8_SCHED;
;             PG8_LDA(At, 0, 1); PG8_STAGE(PG8_SB(0, 0), b2, voffB); PG8_STAGE(PG8_SB(0, 1), b2 + hstep, voffB); PG8_STAGE(PG8_SA(0, 0), a2, voffA);
;             PG8_WAIT_V(8); PG8_WAIT_L(0); PG8_BAR; PG8_MMA(1, 0, At, B0); PG8_MMA(1, 1, At, B1); PG8_BAR; PG8_SCHED;
.LBB0_219:
	s_add_u32 s0, s24, 0xfffc0080
	s_addc_u32 s1, s25, -1
	s_add_i32 s2, 0, 0x10000
	s_cmp_eq_u32 s55, 12
	s_cselect_b32 s29, s7, s1
	s_cselect_b32 s28, s9, s0
	s_cselect_b32 s27, s17, s54
	s_cselect_b32 s26, s19, s53
	s_add_i32 s3, 0, 0x14000
	v_add_u32_e32 v140, s2, v168
	v_add_u32_e32 v174, s3, v168
	ds_read_b128 v[128:131], v140
	ds_read_b128 v[132:135], v140 offset:1024
	ds_read_b128 v[136:139], v140 offset:2048
	ds_read_b128 v[140:143], v140 offset:3072
	ds_read_b128 v[158:161], v174
	ds_read_b128 v[162:165], v174 offset:1024
	ds_read_b128 v[170:173], v174 offset:2048
	ds_read_b128 v[174:177], v174 offset:3072
	v_lshl_add_u64 v[210:211], s[24:25], 0, v[154:155]
	s_add_i32 m0, s41, 0xc000
	ds_read_b128 v[178:181], v169
	ds_read_b128 v[182:185], v169 offset:1024
	ds_read_b128 v[186:189], v169 offset:2048
	ds_read_b128 v[190:193], v169 offset:3072
	ds_read_b128 v[194:197], v169 offset:4096
	ds_read_b128 v[198:201], v169 offset:5120
	ds_read_b128 v[202:205], v169 offset:6144
	ds_read_b128 v[206:209], v169 offset:7168
	global_load_lds_dwordx4 v[210:211], off
	v_lshl_add_u64 v[210:211], s[24:25], 0, v[156:157]
	s_add_i32 m0, s41, 0xe000
	s_nop 0
	global_load_lds_dwordx4 v[210:211], off
	s_waitcnt vmcnt(8)
	s_waitcnt lgkmcnt(0)
	s_barrier
	s_setprio 1
	s_waitcnt lgkmcnt(0)
	v_mfma_f32_16x16x32_bf16 v[124:127], v[128:131], v[178:181], v[124:127]
	v_mfma_f32_16x16x32_bf16 v[120:123], v[136:139], v[178:181], v[120:123]
	v_mfma_f32_16x16x32_bf16 v[108:111], v[128:131], v[186:189], v[108:111]
	v_mfma_f32_16x16x32_bf16 v[104:107], v[136:139], v[186:189], v[104:107]
	v_mfma_f32_16x16x32_bf16 v[92:95], v[128:131], v[194:197], v[92:95]
	v_mfma_f32_16x16x32_bf16 v[88:91], v[136:139], v[194:197], v[88:91]
	v_mfma_f32_16x16x32_bf16 v[76:79], v[128:131], v[202:205], v[76:79]
	v_mfma_f32_16x16x32_bf16 v[72:75], v[136:139], v[202:205], v[72:75]
	v_mfma_f32_16x16x32_bf16 v[124:127], v[132:135], v[182:185], v[124:127]
	v_mfma_f32_16x16x32_bf16 v[120:123], v[140:143], v[182:185], v[120:123]
	v_mfma_f32_16x16x32_bf16 v[108:111], v[132:135], v[190:193], v[108:111]
	v_mfma_f32_16x16x32_bf16 v[104:107], v[140:143], v[190:193], v[104:107]
	v_mfma_f32_16x16x32_bf16 v[92:95], v[132:135], v[198:201], v[92:95]
	v_mfma_f32_16x16x32_bf16 v[88:91], v[140:143], v[198:201], v[88:91]
	v_mfma_f32_16x16x32_bf16 v[76:79], v[132:135], v[206:209], v[76:79]
	v_mfma_f32_16x16x32_bf16 v[72:75], v[140:143], v[206:209], v[72:75]
	v_mfma_f32_16x16x32_bf16 v[116:119], v[158:161], v[178:181], v[116:119]
	v_mfma_f32_16x16x32_bf16 v[112:115], v[170:173], v[178:181], v[112:115]
	v_mfma_f32_16x16x32_bf16 v[100:103], v[158:161], v[186:189], v[100:103]
	v_mfma_f32_16x16x32_bf16 v[96:99], v[170:173], v[186:189], v[96:99]
	v_mfma_f32_16x16x32_bf16 v[84:87], v[158:161], v[194:197], v[84:87]
	v_mfma_f32_16x16x32_bf16 v[80:83], v[170:173], v[194:197], v[80:83]
	v_mfma_f32_16x16x32_bf16 v[68:71], v[158:161], v[202:205], v[68:71]
	v_mfma_f32_16x16x32_bf16 v[64:67], v[170:173], v[202:205], v[64:67]
	v_mfma_f32_16x16x32_bf16 v[116:119], v[162:165], v[182:185], v[116:119]
	v_mfma_f32_16x16x32_bf16 v[112:115], v[174:177], v[182:185], v[112:115]
	v_mfma_f32_16x16x32_bf16 v[100:103], v[162:165], v[190:193], v[100:103]
	v_mfma_f32_16x16x32_bf16 v[96:99], v[174:177], v[190:193], v[96:99]
	v_mfma_f32_16x16x32_bf16 v[84:87], v[162:165], v[198:201], v[84:87]
	v_mfma_f32_16x16x32_bf16 v[80:83], v[174:177], v[198:201], v[80:83]
	v_mfma_f32_16x16x32_bf16 v[68:71], v[162:165], v[206:209], v[68:71]
	v_mfma_f32_16x16x32_bf16 v[64:67], v[174:177], v[206:209], v[64:67]
	s_setprio 0
	s_barrier
	s_add_i32 s0, s2, s40
	v_lshl_add_u64 v[210:211], s[26:27], 0, v[144:145]
	s_mov_b32 m0, s0
	ds_read_b128 v[178:181], v169 offset:16384
	ds_read_b128 v[182:185], v169 offset:17408
	ds_read_b128 v[186:189], v169 offset:18432
	ds_read_b128 v[190:193], v169 offset:19456
	ds_read_b128 v[194:197], v169 offset:20480
	ds_read_b128 v[198:201], v169 offset:21504
	ds_read_b128 v[202:205], v169 offset:22528
	ds_read_b128 v[206:209], v169 offset:23552
	global_load_lds_dwordx4 v[210:211], off
	s_add_i32 m0, s0, 0x2000
	s_add_u32 s0, s26, 0x40000
	v_lshl_add_u64 v[212:213], s[26:27], 0, v[152:153]
	s_addc_u32 s1, s27, 0
	s_add_i32 s2, s3, s40
	global_load_lds_dwordx4 v[212:213], off
	v_lshl_add_u64 v[214:215], s[0:1], 0, v[144:145]
	s_mov_b32 m0, s2
	v_lshl_add_u64 v[216:217], s[28:29], 0, v[150:151]
	global_load_lds_dwordx4 v[214:215], off
	v_lshl_add_u64 v[214:215], s[0:1], 0, v[152:153]
	s_add_i32 m0, s2, 0x2000
	s_nop 0
	global_load_lds_dwordx4 v[214:215], off
	v_lshl_add_u64 v[214:215], s[28:29], 0, v[148:149]
	s_mov_b32 m0, s41
	s_nop 0
	global_load_lds_dwordx4 v[214:215], off
	s_mov_b32 m0, s42
	s_nop 0
	global_load_lds_dwordx4 v[216:217], off
	s_waitcnt vmcnt(8)
	s_waitcnt lgkmcnt(0)
	s_barrier
; #define PG8_STAGE(bufoff, gbase, voff) do { _Pragma("unroll") for (int _i = 0; _i < 2; ++_i) \
;         __builtin_amdgcn_global_load_lds((const unsigned*)((const char*)(gbase) + (voff)[_i]), (PG8_LAS unsigned*)(lds + (bufoff) + ldsw + _i * 8192), 16, 0, 0); } while (0)
; #define PG8_LDA(dst, b, h) do { _Pragma("unroll") for (int m = 0; m < 4; ++m) _Pragma("unroll") for (int k = 0; k < 2; ++k) dst[m][k] = *(const PG8_LAS bf16x8*)(lds + PG8_SA(b, h) + aoff + m * 2048 + k * 1024); } while (0)
; #define PG8_LDB(dst, b, h) do { _Pragma("unroll") for (int n = 0; n < 2; ++n) _Pragma("unroll") for (int k = 0; k < 2; ++k) dst[n][k] = *(const PG8_LAS bf16x8*)(lds + PG8_SB(b, h) + boff + n * 2048 + k * 1024); } while (0)
; #define PG8_MMA(ai, bj, At, Bt) do { __builtin_amdgcn_s_setprio(1); _Pragma("unroll") for (int m = 0; m < 4; ++m) _Pragma("unroll") for (int n = 0; n < 2; ++n) _Pragma("unroll") for (int k = 0; k < 2; ++k) \
;         acc[ai][bj][m][n] = __builtin_amdgcn_mfma_f32_16x16x32_bf16(Bt[n][k], At[m][k], acc[ai][bj][m][n], 0, 0, 0); __builtin_amdgcn_s_setprio(0); } while (0)
; #define PG8_WAIT_V(n) asm volatile("s_waitcnt vmcnt(" #n ")" ::: "memory")
; #define PG8_WAIT_L(n) asm volatile("s_waitcnt lgkmcnt(" #n ")" ::: "memory")
; #define PG8_BAR __builtin_amdgcn_s_barrier()
; #define PG8_SCHED __builtin_amdgcn_sched_barrier(0)
; template <class Epi, class Sched, bool ALIGN_EPI = false, bool SP2 = false>
; __device__ __forceinline__ void gemm_phase(PG8_LAS unsigned char* lds, const Gemm g, const Sched& S, const Epi& E, int tid_in) {
;     ...
;             PG8_WAIT_V(8); PG8_WAIT_L(0); PG8_BAR; PG8_MMA(1, 0, At, B0); PG8_MMA(1, 1, At, B1); PG8_BAR; PG8_SCHED;
;             PG8_LDB(B0, 1, 0); PG8_LDB(B1, 1, 1); PG8_SCHED; PG8_LDA(At, 1, 0); PG8_STAGE(PG8_SA(0, 1), a2 + hstep, voffA);
;             PG8_WAIT_V(8); PG8_WAIT_L(0); PG8_BAR; PG8_MMA(0, 0, At, B0); PG8_MMA(0, 1, At, B1); PG8_BAR; PG8_SCHED;
	s_setprio 1
	s_waitcnt lgkmcnt(0)
	v_mfma_f32_16x16x32_bf16 v[60:63], v[128:131], v[178:181], v[60:63]
	v_mfma_f32_16x16x32_bf16 v[56:59], v[136:139], v[178:181], v[56:59]
	v_mfma_f32_16x16x32_bf16 v[44:47], v[128:131], v[186:189], v[44:47]
	v_mfma_f32_16x16x32_bf16 v[40:43], v[136:139], v[186:189], v[40:43]
	v_mfma_f32_16x16x32_bf16 v[28:31], v[128:131], v[194:197], v[28:31]
	v_mfma_f32_16x16x32_bf16 v[24:27], v[136:139], v[194:197], v[24:27]
	v_mfma_f32_16x16x32_bf16 v[12:15], v[128:131], v[202:205], v[12:15]
	v_mfma_f32_16x16x32_bf16 v[8:11], v[136:139], v[202:205], v[8:11]
	v_mfma_f32_16x16x32_bf16 v[60:63], v[132:135], v[182:185], v[60:63]
	v_mfma_f32_16x16x32_bf16 v[56:59], v[140:143], v[182:185], v[56:59]
	v_mfma_f32_16x16x32_bf16 v[44:47], v[132:135], v[190:193], v[44:47]
	v_mfma_f32_16x16x32_bf16 v[40:43], v[140:143], v[190:193], v[40:43]
	v_mfma_f32_16x16x32_bf16 v[28:31], v[132:135], v[198:201], v[28:31]
	v_mfma_f32_16x16x32_bf16 v[24:27], v[140:143], v[198:201], v[24:27]
	v_mfma_f32_16x16x32_bf16 v[12:15], v[132:135], v[206:209], v[12:15]
	v_mfma_f32_16x16x32_bf16 v[8:11], v[140:143], v[206:209], v[8:11]
	v_mfma_f32_16x16x32_bf16 v[52:55], v[158:161], v[178:181], v[52:55]
	v_mfma_f32_16x16x32_bf16 v[48:51], v[170:173], v[178:181], v[48:51]
	v_mfma_f32_16x16x32_bf16 v[36:39], v[158:161], v[186:189], v[36:39]
	v_mfma_f32_16x16x32_bf16 v[32:35], v[170:173], v[186:189], v[32:35]
	v_mfma_f32_16x16x32_bf16 v[20:23], v[158:161], v[194:197], v[20:23]
	v_mfma_f32_16x16x32_bf16 v[16:19], v[170:173], v[194:197], v[16:19]
	v_mfma_f32_16x16x32_bf16 v[4:7], v[158:161], v[202:205], v[4:7]
	v_mfma_f32_16x16x32_bf16 v[0:3], v[170:173], v[202:205], v[0:3]
	v_mfma_f32_16x16x32_bf16 v[52:55], v[162:165], v[182:185], v[52:55]
	v_mfma_f32_16x16x32_bf16 v[48:51], v[174:177], v[182:185], v[48:51]
	v_mfma_f32_16x16x32_bf16 v[36:39], v[162:165], v[190:193], v[36:39]
	v_mfma_f32_16x16x32_bf16 v[32:35], v[174:177], v[190:193], v[32:35]
	v_mfma_f32_16x16x32_bf16 v[20:23], v[162:165], v[198:201], v[20:23]
	v_mfma_f32_16x16x32_bf16 v[16:19], v[174:177], v[198:201], v[16:19]
	v_mfma_f32_16x16x32_bf16 v[4:7], v[162:165], v[206:209], v[4:7]
	v_mfma_f32_16x16x32_bf16 v[0:3], v[174:177], v[206:209], v[0:3]
	s_setprio 0
	s_barrier
	s_add_i32 s2, 0, 0x18000
	s_add_i32 s3, 0, 0x1c000
	v_add_u32_e32 v140, s2, v168
	v_add_u32_e32 v174, s3, v168
	ds_read_b128 v[128:131], v140
	ds_read_b128 v[132:135], v140 offset:1024
	ds_read_b128 v[136:139], v140 offset:2048
	ds_read_b128 v[140:143], v140 offset:3072
	ds_read_b128 v[158:161], v174
	ds_read_b128 v[162:165], v174 offset:1024
	ds_read_b128 v[170:173], v174 offset:2048
	ds_read_b128 v[174:177], v174 offset:3072
	s_add_u32 s0, s28, 0x40000
	s_addc_u32 s1, s29, 0
	s_mov_b32 m0, s43
	v_lshl_add_u64 v[218:219], s[0:1], 0, v[148:149]
	ds_read_b128 v[178:181], v169 offset:32768
	ds_read_b128 v[182:185], v169 offset:33792
	ds_read_b128 v[186:189], v169 offset:34816
	ds_read_b128 v[190:193], v169 offset:35840
	ds_read_b128 v[194:197], v169 offset:36864
	ds_read_b128 v[198:201], v169 offset:37888
	ds_read_b128 v[202:205], v169 offset:38912
	ds_read_b128 v[206:209], v169 offset:39936
	global_load_lds_dwordx4 v[218:219], off
	v_lshl_add_u64 v[218:219], s[0:1], 0, v[150:151]
	s_mov_b32 m0, s44
	s_nop 0
	global_load_lds_dwordx4 v[218:219], off
	s_waitcnt vmcnt(8)
	s_waitcnt lgkmcnt(0)
	s_barrier
	s_setprio 1
	s_waitcnt lgkmcnt(0)
	v_mfma_f32_16x16x32_bf16 v[124:127], v[128:131], v[178:181], v[124:127]
	v_mfma_f32_16x16x32_bf16 v[120:123], v[136:139], v[178:181], v[120:123]
	v_mfma_f32_16x16x32_bf16 v[108:111], v[128:131], v[186:189], v[108:111]
	v_mfma_f32_16x16x32_bf16 v[104:107], v[136:139], v[186:189], v[104:107]
	v_mfma_f32_16x16x32_bf16 v[92:95], v[128:131], v[194:197], v[92:95]
	v_mfma_f32_16x16x32_bf16 v[88:91], v[136:139], v[194:197], v[88:91]
	v_mfma_f32_16x16x32_bf16 v[76:79], v[128:131], v[202:205], v[76:79]
	v_mfma_f32_16x16x32_bf16 v[72:75], v[136:139], v[202:205], v[72:75]
	v_mfma_f32_16x16x32_bf16 v[124:127], v[132:135], v[182:185], v[124:127]
	v_mfma_f32_16x16x32_bf16 v[120:123], v[140:143], v[182:185], v[120:123]
	v_mfma_f32_16x16x32_bf16 v[108:111], v[132:135], v[190:193], v[108:111]
	v_mfma_f32_16x16x32_bf16 v[104:107], v[140:143], v[190:193], v[104:107]
	v_mfma_f32_16x16x32_bf16 v[92:95], v[132:135], v[198:201], v[92:95]
	v_mfma_f32_16x16x32_bf16 v[88:91], v[140:143], v[198:201], v[88:91]
	v_mfma_f32_16x16x32_bf16 v[76:79], v[132:135], v[206:209], v[76:79]
	v_mfma_f32_16x16x32_bf16 v[72:75], v[140:143], v[206:209], v[72:75]
	v_mfma_f32_16x16x32_bf16 v[116:119], v[158:161], v[178:181], v[116:119]
	v_mfma_f32_16x16x32_bf16 v[112:115], v[170:173], v[178:181], v[112:115]
	v_mfma_f32_16x16x32_bf16 v[100:103], v[158:161], v[186:189], v[100:103]
	v_mfma_f32_16x16x32_bf16 v[96:99], v[170:173], v[186:189], v[96:99]
	v_mfma_f32_16x16x32_bf16 v[84:87], v[158:161], v[194:197], v[84:87]
	v_mfma_f32_16x16x32_bf16 v[80:83], v[170:173], v[194:197], v[80:83]
	v_mfma_f32_16x16x32_bf16 v[68:71], v[158:161], v[202:205], v[68:71]
	v_mfma_f32_16x16x32_bf16 v[64:67], v[170:173], v[202:205], v[64:67]
	v_mfma_f32_16x16x32_bf16 v[116:119], v[162:165], v[182:185], v[116:119]
	v_mfma_f32_16x16x32_bf16 v[112:115], v[174:177], v[182:185], v[112:115]
	v_mfma_f32_16x16x32_bf16 v[100:103], v[162:165], v[190:193], v[100:103]
	v_mfma_f32_16x16x32_bf16 v[96:99], v[174:177], v[190:193], v[96:99]
	v_mfma_f32_16x16x32_bf16 v[84:87], v[162:165], v[198:201], v[84:87]
	v_mfma_f32_16x16x32_bf16 v[80:83], v[174:177], v[198:201], v[80:83]
	v_mfma_f32_16x16x32_bf16 v[68:71], v[162:165], v[206:209], v[68:71]
	v_mfma_f32_16x16x32_bf16 v[64:67], v[174:177], v[206:209], v[64:67]
	s_setprio 0
	s_barrier
; #define PG8_STAGE(bufoff, gbase, voff) do { _Pragma("unroll") for (int _i = 0; _i < 2; ++_i) \
;         __builtin_amdgcn_global_load_lds((const unsigned*)((const char*)(gbase) + (voff)[_i]), (PG8_LAS unsigned*)(lds + (bufoff) + ldsw + _i * 8192), 16, 0, 0); } while (0)
; #define PG8_LDA(dst, b, h) do { _Pragma("unroll") for (int m = 0; m < 4; ++m) _Pragma("unroll") for (int k = 0; k < 2; ++k) dst[m][k] = *(const PG8_LAS bf16x8*)(lds + PG8_SA(b, h) + aoff + m * 2048 + k * 1024); } while (0)
; #define PG8_MMA(ai, bj, At, Bt) do { __builtin_amdgcn_s_setprio(1); _Pragma("unroll") for (int m = 0; m < 4; ++m) _Pragma("unroll") for (int n = 0; n < 2; ++n) _Pragma("unroll") for (int k = 0; k < 2; ++k) \
;         acc[ai][bj][m][n] = __builtin_amdgcn_mfma_f32_16x16x32_bf16(Bt[n][k], At[m][k], acc[ai][bj][m][n], 0, 0, 0); __builtin_amdgcn_s_setprio(0); } while (0)
; #define PG8_WAIT_V(n) asm volatile("s_waitcnt vmcnt(" #n ")" ::: "memory")
; #define PG8_WAIT_L(n) asm volatile("s_waitcnt lgkmcnt(" #n ")" ::: "memory")
; #define PG8_BAR __builtin_amdgcn_s_barrier()
; #define PG8_SCHED __builtin_amdgcn_sched_barrier(0)
; template <class Epi, class Sched, bool ALIGN_EPI = false, bool SP2 = false>
; __device__ __forceinline__ void gemm_phase(PG8_LAS unsigned char* lds, const Gemm g, const Sched& S, const Epi& E, int tid_in) {
;     ...
;         for (int t = 0; t < nt; t += 2) {
;             const bool last = (t == nt - 2);
;             const char* a1 = cA + (size_t)(t + 1) * kstep;
;             const char* a2 = last ? nA : cA + (size_t)(t + 2) * kstep; const char* b2 = last ? nB : cB + (size_t)(t + 2) * kstep;
;             const char* a3 = a2 + kstep; const char* b3 = b2 + kstep;
;     ...
;             PG8_LDA(At, 1, 1); PG8_STAGE(PG8_SB(1, 0), b3, voffB); PG8_STAGE(PG8_SB(1, 1), b3 + hstep, voffB); PG8_STAGE(PG8_SA(1, 0), a3, voffA);
;             PG8_WAIT_V(8); PG8_WAIT_L(0); PG8_BAR; PG8_MMA(1, 0, At, B0); PG8_MMA(1, 1, At, B1); PG8_BAR; PG8_SCHED;
	s_add_i32 s0, s2, s40
	v_lshl_add_u64 v[210:211], v[210:211], 0, s[68:69]
	s_mov_b32 m0, s0
	ds_read_b128 v[178:181], v169 offset:49152
	ds_read_b128 v[182:185], v169 offset:50176
	ds_read_b128 v[186:189], v169 offset:51200
	ds_read_b128 v[190:193], v169 offset:52224
	ds_read_b128 v[194:197], v169 offset:53248
	ds_read_b128 v[198:201], v169 offset:54272
	ds_read_b128 v[202:205], v169 offset:55296
	ds_read_b128 v[206:209], v169 offset:56320
	global_load_lds_dwordx4 v[210:211], off
	s_add_i32 m0, s0, 0x2000
	s_add_u32 s0, s26, 0x40080
	v_lshl_add_u64 v[210:211], v[212:213], 0, s[68:69]
	s_addc_u32 s1, s27, 0
	s_add_i32 s2, s3, s40
	global_load_lds_dwordx4 v[210:211], off
	v_lshl_add_u64 v[210:211], s[0:1], 0, v[144:145]
	s_mov_b32 m0, s2
	s_nop 0
	global_load_lds_dwordx4 v[210:211], off
	v_lshl_add_u64 v[210:211], s[0:1], 0, v[152:153]
	s_add_i32 m0, s2, 0x2000
	s_nop 0
	global_load_lds_dwordx4 v[210:211], off
	v_lshl_add_u64 v[210:211], v[214:215], 0, s[68:69]
	s_mov_b32 m0, s50
	s_nop 0
	global_load_lds_dwordx4 v[210:211], off
	v_lshl_add_u64 v[210:211], v[216:217], 0, s[68:69]
	s_mov_b32 m0, s51
	s_nop 0
	global_load_lds_dwordx4 v[210:211], off
	s_waitcnt vmcnt(8)
	s_waitcnt lgkmcnt(0)
	s_barrier
	s_setprio 1
	s_waitcnt lgkmcnt(0)
	v_mfma_f32_16x16x32_bf16 v[60:63], v[128:131], v[178:181], v[60:63]
	v_mfma_f32_16x16x32_bf16 v[56:59], v[136:139], v[178:181], v[56:59]
	v_mfma_f32_16x16x32_bf16 v[44:47], v[128:131], v[186:189], v[44:47]
	v_mfma_f32_16x16x32_bf16 v[40:43], v[136:139], v[186:189], v[40:43]
	v_mfma_f32_16x16x32_bf16 v[28:31], v[128:131], v[194:197], v[28:31]
	v_mfma_f32_16x16x32_bf16 v[24:27], v[136:139], v[194:197], v[24:27]
	v_mfma_f32_16x16x32_bf16 v[12:15], v[128:131], v[202:205], v[12:15]
	v_mfma_f32_16x16x32_bf16 v[8:11], v[136:139], v[202:205], v[8:11]
	v_mfma_f32_16x16x32_bf16 v[60:63], v[132:135], v[182:185], v[60:63]
	v_mfma_f32_16x16x32_bf16 v[56:59], v[140:143], v[182:185], v[56:59]
	v_mfma_f32_16x16x32_bf16 v[44:47], v[132:135], v[190:193], v[44:47]
	v_mfma_f32_16x16x32_bf16 v[40:43], v[140:143], v[190:193], v[40:43]
	v_mfma_f32_16x16x32_bf16 v[28:31], v[132:135], v[198:201], v[28:31]
	v_mfma_f32_16x16x32_bf16 v[24:27], v[140:143], v[198:201], v[24:27]
	v_mfma_f32_16x16x32_bf16 v[12:15], v[132:135], v[206:209], v[12:15]
	v_mfma_f32_16x16x32_bf16 v[8:11], v[140:143], v[206:209], v[8:11]
	v_mfma_f32_16x16x32_bf16 v[52:55], v[158:161], v[178:181], v[52:55]
	v_mfma_f32_16x16x32_bf16 v[48:51], v[170:173], v[178:181], v[48:51]
	v_mfma_f32_16x16x32_bf16 v[36:39], v[158:161], v[186:189], v[36:39]
	v_mfma_f32_16x16x32_bf16 v[32:35], v[170:173], v[186:189], v[32:35]
	v_mfma_f32_16x16x32_bf16 v[20:23], v[158:161], v[194:197], v[20:23]
	v_mfma_f32_16x16x32_bf16 v[16:19], v[170:173], v[194:197], v[16:19]
	v_mfma_f32_16x16x32_bf16 v[4:7], v[158:161], v[202:205], v[4:7]
	v_mfma_f32_16x16x32_bf16 v[0:3], v[170:173], v[202:205], v[0:3]
	v_mfma_f32_16x16x32_bf16 v[52:55], v[162:165], v[182:185], v[52:55]
	v_mfma_f32_16x16x32_bf16 v[48:51], v[174:177], v[182:185], v[48:51]
	v_mfma_f32_16x16x32_bf16 v[36:39], v[162:165], v[190:193], v[36:39]
	v_mfma_f32_16x16x32_bf16 v[32:35], v[174:177], v[190:193], v[32:35]
	v_mfma_f32_16x16x32_bf16 v[20:23], v[162:165], v[198:201], v[20:23]
	v_mfma_f32_16x16x32_bf16 v[16:19], v[174:177], v[198:201], v[16:19]
	v_mfma_f32_16x16x32_bf16 v[4:7], v[162:165], v[206:209], v[4:7]
	v_mfma_f32_16x16x32_bf16 v[0:3], v[174:177], v[206:209], v[0:3]
	s_setprio 0
	s_barrier
	s_add_i32 s55, s55, 2
	s_add_u32 s24, s24, 0x100
	s_addc_u32 s25, s25, 0
	s_add_u32 s53, s53, 0x100
	s_addc_u32 s54, s54, 0
	s_cmp_gt_u32 s55, 13
	s_cbranch_scc0 .LBB0_219
	s_and_b64 vcc, exec, s[14:15]
	s_cbranch_vccz .LBB0_222
	s_barrier

; #define PG8_STAGE(bufoff, gbase, voff) do { _Pragma("unroll") for (int _i = 0; _i < 2; ++_i) \
;         __builtin_amdgcn_global_load_lds((const unsigned*)((const char*)(gbase) + (voff)[_i]), (PG8_LAS unsigned*)(lds + (bufoff) + ldsw + _i * 8192), 16, 0, 0); } while (0)
; #define PG8_LDA(dst, b, h) do { _Pragma("unroll") for (int m = 0; m < 4; ++m) _Pragma("unroll") for (int k = 0; k < 2; ++k) dst[m][k] = *(const PG8_LAS bf16x8*)(lds + PG8_SA(b, h) + aoff + m * 2048 + k * 1024); } while (0)
; #define PG8_LDB(dst, b, h) do { _Pragma("unroll") for (int n = 0; n < 2; ++n) _Pragma("unroll") for (int k = 0; k < 2; ++k) dst[n][k] = *(const PG8_LAS bf16x8*)(lds + PG8_SB(b, h) + boff + n * 2048 + k * 1024); } while (0)
; #define PG8_MMA(ai, bj, At, Bt) do { __builtin_amdgcn_s_setprio(1); _Pragma("unroll") for (int m = 0; m < 4; ++m) _Pragma("unroll") for (int n = 0; n < 2; ++n) _Pragma("unroll") for (int k = 0; k < 2; ++k) \
;         acc[ai][bj][m][n] = __builtin_amdgcn_mfma_f32_16x16x32_bf16(Bt[n][k], At[m][k], acc[ai][bj][m][n], 0, 0, 0); __builtin_amdgcn_s_setprio(0); } while (0)
; #define PG8_WAIT_V(n) asm volatile("s_waitcnt vmcnt(" #n ")" ::: "memory")
; #define PG8_WAIT_L(n) asm volatile("s_waitcnt lgkmcnt(" #n ")" ::: "memory")
; #define PG8_BAR __builtin_amdgcn_s_barrier()
; #define PG8_SCHED __builtin_amdgcn_sched_barrier(0)
; template <class Epi, class Sched, bool ALIGN_EPI = false, bool SP2 = false>
; __device__ __forceinline__ void gemm_phase(PG8_LAS unsigned char* lds, const Gemm g, const Sched& S, const Epi& E, int tid_in) {
;     ...
;             PG8_LDB(B0, 0, 0); PG8_LDB(B1, 0, 1); PG8_SCHED; PG8_LDA(At, 0, 0); PG8_STAGE(PG8_SA(1, 1), a1 + hstep, voffA);
;             PG8_WAIT_V(8); PG8_WAIT_L(0); PG8_BAR; PG8_MMA(0, 0, At, B0); PG8_MMA(0, 1, At, B1); PG8_BAR; PG8_SCHED;
;             PG8_LDA(At, 0, 1); PG8_STAGE(PG8_SB(0, 0), b2, voffB); PG8_STAGE(PG8_SB(0, 1), b2 + hstep, voffB); PG8_STAGE(PG8_SA(0, 0), a2, voffA);
;             PG8_WAIT_V(8); PG8_WAIT_L(0); PG8_BAR; PG8_MMA(1, 0, At, B0); PG8_MMA(1, 1, At, B1); PG8_BAR; PG8_SCHED;
.LBB0_307:
	s_add_i32 s1, s0, 2
	s_add_u32 s26, s24, 0x80
	s_addc_u32 s27, s25, 0
	s_add_i32 s33, 0, 0x10000
	s_cmp_eq_u32 s67, s0
	s_cselect_b32 s27, s19, s27
	s_cselect_b32 s26, s18, s26
	v_add_u32_e32 v143, s33, v232
	s_cselect_b32 s71, s21, s69
	s_cselect_b32 s70, s20, s68
	s_add_i32 s0, 0, 0x14000
	s_waitcnt lgkmcnt(0)
	ds_read_b128 v[128:131], v143
	ds_read_b128 v[132:135], v143 offset:1024
	ds_read_b128 v[154:157], v143 offset:2048
	ds_read_b128 v[158:161], v143 offset:3072
	v_add_u32_e32 v143, s0, v232
	ds_read_b128 v[162:165], v143
	ds_read_b128 v[166:169], v143 offset:1024
	ds_read_b128 v[170:173], v143 offset:2048
	ds_read_b128 v[174:177], v143 offset:3072
	v_lshl_add_u64 v[210:211], s[24:25], 0, v[150:151]
	s_add_i32 m0, s23, 0xc000
	ds_read_b128 v[178:181], v233
	ds_read_b128 v[182:185], v233 offset:1024
	ds_read_b128 v[186:189], v233 offset:2048
	ds_read_b128 v[190:193], v233 offset:3072
	ds_read_b128 v[194:197], v233 offset:4096
	ds_read_b128 v[198:201], v233 offset:5120
	ds_read_b128 v[202:205], v233 offset:6144
	ds_read_b128 v[206:209], v233 offset:7168
	global_load_lds_dwordx4 v[210:211], off
	v_lshl_add_u64 v[210:211], s[24:25], 0, v[152:153]
	s_add_i32 m0, s23, 0xe000
	s_nop 0
	global_load_lds_dwordx4 v[210:211], off
	s_waitcnt vmcnt(8)
	s_waitcnt lgkmcnt(0)
	s_barrier
	s_setprio 1
	s_waitcnt lgkmcnt(0)
	v_mfma_f32_16x16x32_bf16 v[124:127], v[128:131], v[178:181], v[124:127]
	v_mfma_f32_16x16x32_bf16 v[120:123], v[154:157], v[178:181], v[120:123]
	v_mfma_f32_16x16x32_bf16 v[116:119], v[128:131], v[186:189], v[116:119]
	v_mfma_f32_16x16x32_bf16 v[112:115], v[154:157], v[186:189], v[112:115]
	v_mfma_f32_16x16x32_bf16 v[108:111], v[128:131], v[194:197], v[108:111]
	v_mfma_f32_16x16x32_bf16 v[104:107], v[154:157], v[194:197], v[104:107]
	v_mfma_f32_16x16x32_bf16 v[100:103], v[128:131], v[202:205], v[100:103]
	v_mfma_f32_16x16x32_bf16 v[96:99], v[154:157], v[202:205], v[96:99]
	v_mfma_f32_16x16x32_bf16 v[124:127], v[132:135], v[182:185], v[124:127]
	v_mfma_f32_16x16x32_bf16 v[120:123], v[158:161], v[182:185], v[120:123]
	v_mfma_f32_16x16x32_bf16 v[116:119], v[132:135], v[190:193], v[116:119]
	v_mfma_f32_16x16x32_bf16 v[112:115], v[158:161], v[190:193], v[112:115]
	v_mfma_f32_16x16x32_bf16 v[108:111], v[132:135], v[198:201], v[108:111]
	v_mfma_f32_16x16x32_bf16 v[104:107], v[158:161], v[198:201], v[104:107]
	v_mfma_f32_16x16x32_bf16 v[100:103], v[132:135], v[206:209], v[100:103]
	v_mfma_f32_16x16x32_bf16 v[96:99], v[158:161], v[206:209], v[96:99]
	v_mfma_f32_16x16x32_bf16 v[60:63], v[162:165], v[178:181], v[60:63]
	v_mfma_f32_16x16x32_bf16 v[56:59], v[170:173], v[178:181], v[56:59]
	v_mfma_f32_16x16x32_bf16 v[52:55], v[162:165], v[186:189], v[52:55]
	v_mfma_f32_16x16x32_bf16 v[48:51], v[170:173], v[186:189], v[48:51]
	v_mfma_f32_16x16x32_bf16 v[44:47], v[162:165], v[194:197], v[44:47]
	v_mfma_f32_16x16x32_bf16 v[40:43], v[170:173], v[194:197], v[40:43]
	v_mfma_f32_16x16x32_bf16 v[36:39], v[162:165], v[202:205], v[36:39]
	v_mfma_f32_16x16x32_bf16 v[32:35], v[170:173], v[202:205], v[32:35]
	v_mfma_f32_16x16x32_bf16 v[60:63], v[166:169], v[182:185], v[60:63]
	v_mfma_f32_16x16x32_bf16 v[56:59], v[174:177], v[182:185], v[56:59]
	v_mfma_f32_16x16x32_bf16 v[52:55], v[166:169], v[190:193], v[52:55]
	v_mfma_f32_16x16x32_bf16 v[48:51], v[174:177], v[190:193], v[48:51]
	v_mfma_f32_16x16x32_bf16 v[44:47], v[166:169], v[198:201], v[44:47]
	v_mfma_f32_16x16x32_bf16 v[40:43], v[174:177], v[198:201], v[40:43]
	v_mfma_f32_16x16x32_bf16 v[36:39], v[166:169], v[206:209], v[36:39]
	v_mfma_f32_16x16x32_bf16 v[32:35], v[174:177], v[206:209], v[32:35]
	s_setprio 0
	s_barrier
	s_add_i32 s33, s33, s31
	v_lshl_add_u64 v[210:211], s[70:71], 0, v[144:145]
	s_mov_b32 m0, s33
	ds_read_b128 v[178:181], v233 offset:16384
	ds_read_b128 v[182:185], v233 offset:17408
	ds_read_b128 v[186:189], v233 offset:18432
	ds_read_b128 v[190:193], v233 offset:19456
	ds_read_b128 v[194:197], v233 offset:20480
	ds_read_b128 v[198:201], v233 offset:21504
	ds_read_b128 v[202:205], v233 offset:22528
	ds_read_b128 v[206:209], v233 offset:23552
	global_load_lds_dwordx4 v[210:211], off
	s_add_i32 m0, s33, 0x2000
	v_lshl_add_u64 v[212:213], s[70:71], 0, v[140:141]
	s_add_u32 s70, s70, s90
	s_addc_u32 s71, s71, 0
	s_add_i32 s0, s0, s31
	global_load_lds_dwordx4 v[212:213], off
	v_lshl_add_u64 v[214:215], s[70:71], 0, v[144:145]
	s_mov_b32 m0, s0
	v_lshl_add_u64 v[216:217], s[70:71], 0, v[140:141]
	global_load_lds_dwordx4 v[214:215], off
	s_add_i32 m0, s0, 0x2000
	v_lshl_add_u64 v[218:219], s[26:27], 0, v[136:137]
	global_load_lds_dwordx4 v[216:217], off
	s_mov_b32 m0, s23
	v_lshl_add_u64 v[234:235], s[26:27], 0, v[138:139]
	global_load_lds_dwordx4 v[218:219], off
	s_mov_b32 m0, s41
	s_nop 0
	global_load_lds_dwordx4 v[234:235], off
	s_waitcnt vmcnt(8)
	s_waitcnt lgkmcnt(0)
	s_barrier
; #define PG8_STAGE(bufoff, gbase, voff) do { _Pragma("unroll") for (int _i = 0; _i < 2; ++_i) \
;         __builtin_amdgcn_global_load_lds((const unsigned*)((const char*)(gbase) + (voff)[_i]), (PG8_LAS unsigned*)(lds + (bufoff) + ldsw + _i * 8192), 16, 0, 0); } while (0)
; #define PG8_LDA(dst, b, h) do { _Pragma("unroll") for (int m = 0; m < 4; ++m) _Pragma("unroll") for (int k = 0; k < 2; ++k) dst[m][k] = *(const PG8_LAS bf16x8*)(lds + PG8_SA(b, h) + aoff + m * 2048 + k * 1024); } while (0)
; #define PG8_LDB(dst, b, h) do { _Pragma("unroll") for (int n = 0; n < 2; ++n) _Pragma("unroll") for (int k = 0; k < 2; ++k) dst[n][k] = *(const PG8_LAS bf16x8*)(lds + PG8_SB(b, h) + boff + n * 2048 + k * 1024); } while (0)
; #define PG8_MMA(ai, bj, At, Bt) do { __builtin_amdgcn_s_setprio(1); _Pragma("unroll") for (int m = 0; m < 4; ++m) _Pragma("unroll") for (int n = 0; n < 2; ++n) _Pragma("unroll") for (int k = 0; k < 2; ++k) \
;         acc[ai][bj][m][n] = __builtin_amdgcn_mfma_f32_16x16x32_bf16(Bt[n][k], At[m][k], acc[ai][bj][m][n], 0, 0, 0); __builtin_amdgcn_s_setprio(0); } while (0)
; #define PG8_WAIT_V(n) asm volatile("s_waitcnt vmcnt(" #n ")" ::: "memory")
; #define PG8_WAIT_L(n) asm volatile("s_waitcnt lgkmcnt(" #n ")" ::: "memory")
; #define PG8_BAR __builtin_amdgcn_s_barrier()
; #define PG8_SCHED __builtin_amdgcn_sched_barrier(0)
; template <class Epi, class Sched, bool ALIGN_EPI = false, bool SP2 = false>
; __device__ __forceinline__ void gemm_phase(PG8_LAS unsigned char* lds, const Gemm g, const Sched& S, const Epi& E, int tid_in) {
;     ...
;             PG8_WAIT_V(8); PG8_WAIT_L(0); PG8_BAR; PG8_MMA(1, 0, At, B0); PG8_MMA(1, 1, At, B1); PG8_BAR; PG8_SCHED;
;             PG8_LDB(B0, 1, 0); PG8_LDB(B1, 1, 1); PG8_SCHED; PG8_LDA(At, 1, 0); PG8_STAGE(PG8_SA(0, 1), a2 + hstep, voffA);
;             PG8_WAIT_V(8); PG8_WAIT_L(0); PG8_BAR; PG8_MMA(0, 0, At, B0); PG8_MMA(0, 1, At, B1); PG8_BAR; PG8_SCHED;
	s_setprio 1
	s_waitcnt lgkmcnt(0)
	v_mfma_f32_16x16x32_bf16 v[92:95], v[128:131], v[178:181], v[92:95]
	v_mfma_f32_16x16x32_bf16 v[88:91], v[154:157], v[178:181], v[88:91]
	v_mfma_f32_16x16x32_bf16 v[84:87], v[128:131], v[186:189], v[84:87]
	v_mfma_f32_16x16x32_bf16 v[80:83], v[154:157], v[186:189], v[80:83]
	v_mfma_f32_16x16x32_bf16 v[76:79], v[128:131], v[194:197], v[76:79]
	v_mfma_f32_16x16x32_bf16 v[72:75], v[154:157], v[194:197], v[72:75]
	v_mfma_f32_16x16x32_bf16 v[68:71], v[128:131], v[202:205], v[68:71]
	v_mfma_f32_16x16x32_bf16 v[64:67], v[154:157], v[202:205], v[64:67]
	v_mfma_f32_16x16x32_bf16 v[92:95], v[132:135], v[182:185], v[92:95]
	v_mfma_f32_16x16x32_bf16 v[88:91], v[158:161], v[182:185], v[88:91]
	v_mfma_f32_16x16x32_bf16 v[84:87], v[132:135], v[190:193], v[84:87]
	v_mfma_f32_16x16x32_bf16 v[80:83], v[158:161], v[190:193], v[80:83]
	v_mfma_f32_16x16x32_bf16 v[76:79], v[132:135], v[198:201], v[76:79]
	v_mfma_f32_16x16x32_bf16 v[72:75], v[158:161], v[198:201], v[72:75]
	v_mfma_f32_16x16x32_bf16 v[68:71], v[132:135], v[206:209], v[68:71]
	v_mfma_f32_16x16x32_bf16 v[64:67], v[158:161], v[206:209], v[64:67]
	v_mfma_f32_16x16x32_bf16 v[28:31], v[162:165], v[178:181], v[28:31]
	v_mfma_f32_16x16x32_bf16 v[24:27], v[170:173], v[178:181], v[24:27]
	v_mfma_f32_16x16x32_bf16 v[20:23], v[162:165], v[186:189], v[20:23]
	v_mfma_f32_16x16x32_bf16 v[16:19], v[170:173], v[186:189], v[16:19]
	v_mfma_f32_16x16x32_bf16 v[12:15], v[162:165], v[194:197], v[12:15]
	v_mfma_f32_16x16x32_bf16 v[8:11], v[170:173], v[194:197], v[8:11]
	v_mfma_f32_16x16x32_bf16 v[4:7], v[162:165], v[202:205], v[4:7]
	v_mfma_f32_16x16x32_bf16 v[0:3], v[170:173], v[202:205], v[0:3]
	v_mfma_f32_16x16x32_bf16 v[28:31], v[166:169], v[182:185], v[28:31]
	v_mfma_f32_16x16x32_bf16 v[24:27], v[174:177], v[182:185], v[24:27]
	v_mfma_f32_16x16x32_bf16 v[20:23], v[166:169], v[190:193], v[20:23]
	v_mfma_f32_16x16x32_bf16 v[16:19], v[174:177], v[190:193], v[16:19]
	v_mfma_f32_16x16x32_bf16 v[12:15], v[166:169], v[198:201], v[12:15]
	v_mfma_f32_16x16x32_bf16 v[8:11], v[174:177], v[198:201], v[8:11]
	v_mfma_f32_16x16x32_bf16 v[4:7], v[166:169], v[206:209], v[4:7]
	v_mfma_f32_16x16x32_bf16 v[0:3], v[174:177], v[206:209], v[0:3]
	s_setprio 0
	s_barrier
	s_add_i32 s0, 0, 0x18000
	v_add_u32_e32 v143, s0, v232
	s_add_i32 s33, 0, 0x1c000
	ds_read_b128 v[128:131], v143
	ds_read_b128 v[132:135], v143 offset:1024
	ds_read_b128 v[154:157], v143 offset:2048
	ds_read_b128 v[158:161], v143 offset:3072
	v_add_u32_e32 v143, s33, v232
	ds_read_b128 v[162:165], v143
	ds_read_b128 v[166:169], v143 offset:1024
	ds_read_b128 v[170:173], v143 offset:2048
	ds_read_b128 v[174:177], v143 offset:3072
	s_add_u32 s26, s26, s90
	s_addc_u32 s27, s27, 0
	s_mov_b32 m0, s42
	v_lshl_add_u64 v[236:237], s[26:27], 0, v[136:137]
	ds_read_b128 v[178:181], v233 offset:32768
	ds_read_b128 v[182:185], v233 offset:33792
	ds_read_b128 v[186:189], v233 offset:34816
	ds_read_b128 v[190:193], v233 offset:35840
	ds_read_b128 v[194:197], v233 offset:36864
	ds_read_b128 v[198:201], v233 offset:37888
	ds_read_b128 v[202:205], v233 offset:38912
	ds_read_b128 v[206:209], v233 offset:39936
	global_load_lds_dwordx4 v[236:237], off
	v_lshl_add_u64 v[236:237], s[26:27], 0, v[138:139]
	s_mov_b32 m0, s43
	s_nop 0
	global_load_lds_dwordx4 v[236:237], off
	s_waitcnt vmcnt(8)
	s_waitcnt lgkmcnt(0)
	s_barrier
	s_setprio 1
	s_waitcnt lgkmcnt(0)
	v_mfma_f32_16x16x32_bf16 v[124:127], v[128:131], v[178:181], v[124:127]
	v_mfma_f32_16x16x32_bf16 v[120:123], v[154:157], v[178:181], v[120:123]
	v_mfma_f32_16x16x32_bf16 v[116:119], v[128:131], v[186:189], v[116:119]
	v_mfma_f32_16x16x32_bf16 v[112:115], v[154:157], v[186:189], v[112:115]
	v_mfma_f32_16x16x32_bf16 v[108:111], v[128:131], v[194:197], v[108:111]
	v_mfma_f32_16x16x32_bf16 v[104:107], v[154:157], v[194:197], v[104:107]
	v_mfma_f32_16x16x32_bf16 v[100:103], v[128:131], v[202:205], v[100:103]
	v_mfma_f32_16x16x32_bf16 v[96:99], v[154:157], v[202:205], v[96:99]
	v_mfma_f32_16x16x32_bf16 v[124:127], v[132:135], v[182:185], v[124:127]
	v_mfma_f32_16x16x32_bf16 v[120:123], v[158:161], v[182:185], v[120:123]
	v_mfma_f32_16x16x32_bf16 v[116:119], v[132:135], v[190:193], v[116:119]
	v_mfma_f32_16x16x32_bf16 v[112:115], v[158:161], v[190:193], v[112:115]
	v_mfma_f32_16x16x32_bf16 v[108:111], v[132:135], v[198:201], v[108:111]
	v_mfma_f32_16x16x32_bf16 v[104:107], v[158:161], v[198:201], v[104:107]
	v_mfma_f32_16x16x32_bf16 v[100:103], v[132:135], v[206:209], v[100:103]
	v_mfma_f32_16x16x32_bf16 v[96:99], v[158:161], v[206:209], v[96:99]
	v_mfma_f32_16x16x32_bf16 v[60:63], v[162:165], v[178:181], v[60:63]
	v_mfma_f32_16x16x32_bf16 v[56:59], v[170:173], v[178:181], v[56:59]
	v_mfma_f32_16x16x32_bf16 v[52:55], v[162:165], v[186:189], v[52:55]
	v_mfma_f32_16x16x32_bf16 v[48:51], v[170:173], v[186:189], v[48:51]
	v_mfma_f32_16x16x32_bf16 v[44:47], v[162:165], v[194:197], v[44:47]
	v_mfma_f32_16x16x32_bf16 v[40:43], v[170:173], v[194:197], v[40:43]
	v_mfma_f32_16x16x32_bf16 v[36:39], v[162:165], v[202:205], v[36:39]
	v_mfma_f32_16x16x32_bf16 v[32:35], v[170:173], v[202:205], v[32:35]
	v_mfma_f32_16x16x32_bf16 v[60:63], v[166:169], v[182:185], v[60:63]
	v_mfma_f32_16x16x32_bf16 v[56:59], v[174:177], v[182:185], v[56:59]
	v_mfma_f32_16x16x32_bf16 v[52:55], v[166:169], v[190:193], v[52:55]
	v_mfma_f32_16x16x32_bf16 v[48:51], v[174:177], v[190:193], v[48:51]
	v_mfma_f32_16x16x32_bf16 v[44:47], v[166:169], v[198:201], v[44:47]
	v_mfma_f32_16x16x32_bf16 v[40:43], v[174:177], v[198:201], v[40:43]
	v_mfma_f32_16x16x32_bf16 v[36:39], v[166:169], v[206:209], v[36:39]
	v_mfma_f32_16x16x32_bf16 v[32:35], v[174:177], v[206:209], v[32:35]
	s_setprio 0
	s_barrier
; #define PG8_STAGE(bufoff, gbase, voff) do { _Pragma("unroll") for (int _i = 0; _i < 2; ++_i) \
;         __builtin_amdgcn_global_load_lds((const unsigned*)((const char*)(gbase) + (voff)[_i]), (PG8_LAS unsigned*)(lds + (bufoff) + ldsw + _i * 8192), 16, 0, 0); } while (0)
; #define PG8_LDA(dst, b, h) do { _Pragma("unroll") for (int m = 0; m < 4; ++m) _Pragma("unroll") for (int k = 0; k < 2; ++k) dst[m][k] = *(const PG8_LAS bf16x8*)(lds + PG8_SA(b, h) + aoff + m * 2048 + k * 1024); } while (0)
; #define PG8_MMA(ai, bj, At, Bt) do { __builtin_amdgcn_s_setprio(1); _Pragma("unroll") for (int m = 0; m < 4; ++m) _Pragma("unroll") for (int n = 0; n < 2; ++n) _Pragma("unroll") for (int k = 0; k < 2; ++k) \
;         acc[ai][bj][m][n] = __builtin_amdgcn_mfma_f32_16x16x32_bf16(Bt[n][k], At[m][k], acc[ai][bj][m][n], 0, 0, 0); __builtin_amdgcn_s_setprio(0); } while (0)
; #define PG8_WAIT_V(n) asm volatile("s_waitcnt vmcnt(" #n ")" ::: "memory")
; #define PG8_WAIT_L(n) asm volatile("s_waitcnt lgkmcnt(" #n ")" ::: "memory")
; #define PG8_BAR __builtin_amdgcn_s_barrier()
; #define PG8_SCHED __builtin_amdgcn_sched_barrier(0)
; template <class Epi, class Sched, bool ALIGN_EPI = false, bool SP2 = false>
; __device__ __forceinline__ void gemm_phase(PG8_LAS unsigned char* lds, const Gemm g, const Sched& S, const Epi& E, int tid_in) {
;     ...
;         for (int t = 0; t < nt; t += 2) {
;             const bool last = (t == nt - 2);
;             const char* a1 = cA + (size_t)(t + 1) * kstep;
;             const char* a2 = last ? nA : cA + (size_t)(t + 2) * kstep; const char* b2 = last ? nB : cB + (size_t)(t + 2) * kstep;
;             const char* a3 = a2 + kstep; const char* b3 = b2 + kstep;
;     ...
;             PG8_LDA(At, 1, 1); PG8_STAGE(PG8_SB(1, 0), b3, voffB); PG8_STAGE(PG8_SB(1, 1), b3 + hstep, voffB); PG8_STAGE(PG8_SA(1, 0), a3, voffA);
;             PG8_WAIT_V(8); PG8_WAIT_L(0); PG8_BAR; PG8_MMA(1, 0, At, B0); PG8_MMA(1, 1, At, B1); PG8_BAR; PG8_SCHED;
	s_add_i32 s0, s0, s31
	v_lshl_add_u64 v[210:211], v[210:211], 0, vcc
	s_mov_b32 m0, s0
	ds_read_b128 v[178:181], v233 offset:49152
	ds_read_b128 v[182:185], v233 offset:50176
	ds_read_b128 v[186:189], v233 offset:51200
	ds_read_b128 v[190:193], v233 offset:52224
	ds_read_b128 v[194:197], v233 offset:53248
	ds_read_b128 v[198:201], v233 offset:54272
	ds_read_b128 v[202:205], v233 offset:55296
	ds_read_b128 v[206:209], v233 offset:56320
	global_load_lds_dwordx4 v[210:211], off
	v_lshl_add_u64 v[210:211], v[212:213], 0, vcc
	s_add_i32 m0, s0, 0x2000
	s_add_i32 s0, s33, s31
	global_load_lds_dwordx4 v[210:211], off
	v_lshl_add_u64 v[210:211], v[214:215], 0, vcc
	s_mov_b32 m0, s0
	s_nop 0
	global_load_lds_dwordx4 v[210:211], off
	v_lshl_add_u64 v[210:211], v[216:217], 0, vcc
	s_add_i32 m0, s0, 0x2000
	s_nop 0
	global_load_lds_dwordx4 v[210:211], off
	v_lshl_add_u64 v[210:211], v[218:219], 0, vcc
	s_mov_b32 m0, s53
	s_nop 0
	global_load_lds_dwordx4 v[210:211], off
	v_lshl_add_u64 v[210:211], v[234:235], 0, vcc
	s_mov_b32 m0, s54
	s_nop 0
	global_load_lds_dwordx4 v[210:211], off
	s_waitcnt vmcnt(8)
	s_waitcnt lgkmcnt(0)
	s_barrier
	s_setprio 1
	s_waitcnt lgkmcnt(0)
	v_mfma_f32_16x16x32_bf16 v[92:95], v[128:131], v[178:181], v[92:95]
	v_mfma_f32_16x16x32_bf16 v[88:91], v[154:157], v[178:181], v[88:91]
	v_mfma_f32_16x16x32_bf16 v[84:87], v[128:131], v[186:189], v[84:87]
	v_mfma_f32_16x16x32_bf16 v[80:83], v[154:157], v[186:189], v[80:83]
	v_mfma_f32_16x16x32_bf16 v[76:79], v[128:131], v[194:197], v[76:79]
	v_mfma_f32_16x16x32_bf16 v[72:75], v[154:157], v[194:197], v[72:75]
	v_mfma_f32_16x16x32_bf16 v[68:71], v[128:131], v[202:205], v[68:71]
	v_mfma_f32_16x16x32_bf16 v[64:67], v[154:157], v[202:205], v[64:67]
	v_mfma_f32_16x16x32_bf16 v[92:95], v[132:135], v[182:185], v[92:95]
	v_mfma_f32_16x16x32_bf16 v[88:91], v[158:161], v[182:185], v[88:91]
	v_mfma_f32_16x16x32_bf16 v[84:87], v[132:135], v[190:193], v[84:87]
	v_mfma_f32_16x16x32_bf16 v[80:83], v[158:161], v[190:193], v[80:83]
	v_mfma_f32_16x16x32_bf16 v[76:79], v[132:135], v[198:201], v[76:79]
	v_mfma_f32_16x16x32_bf16 v[72:75], v[158:161], v[198:201], v[72:75]
	v_mfma_f32_16x16x32_bf16 v[68:71], v[132:135], v[206:209], v[68:71]
	v_mfma_f32_16x16x32_bf16 v[64:67], v[158:161], v[206:209], v[64:67]
	v_mfma_f32_16x16x32_bf16 v[28:31], v[162:165], v[178:181], v[28:31]
	v_mfma_f32_16x16x32_bf16 v[24:27], v[170:173], v[178:181], v[24:27]
	v_mfma_f32_16x16x32_bf16 v[20:23], v[162:165], v[186:189], v[20:23]
	v_mfma_f32_16x16x32_bf16 v[16:19], v[170:173], v[186:189], v[16:19]
	v_mfma_f32_16x16x32_bf16 v[12:15], v[162:165], v[194:197], v[12:15]
	v_mfma_f32_16x16x32_bf16 v[8:11], v[170:173], v[194:197], v[8:11]
	v_mfma_f32_16x16x32_bf16 v[4:7], v[162:165], v[202:205], v[4:7]
	v_mfma_f32_16x16x32_bf16 v[0:3], v[170:173], v[202:205], v[0:3]
	v_mfma_f32_16x16x32_bf16 v[28:31], v[166:169], v[182:185], v[28:31]
	v_mfma_f32_16x16x32_bf16 v[24:27], v[174:177], v[182:185], v[24:27]
	v_mfma_f32_16x16x32_bf16 v[20:23], v[166:169], v[190:193], v[20:23]
	v_mfma_f32_16x16x32_bf16 v[16:19], v[174:177], v[190:193], v[16:19]
	v_mfma_f32_16x16x32_bf16 v[12:15], v[166:169], v[198:201], v[12:15]
	v_mfma_f32_16x16x32_bf16 v[8:11], v[174:177], v[198:201], v[8:11]
	v_mfma_f32_16x16x32_bf16 v[4:7], v[166:169], v[206:209], v[4:7]
	v_mfma_f32_16x16x32_bf16 v[0:3], v[174:177], v[206:209], v[0:3]
	s_setprio 0
	s_barrier
	s_add_u32 s24, s24, 0x100
	s_addc_u32 s25, s25, 0
	s_add_u32 s68, s68, 0x100
	s_addc_u32 s69, s69, 0
	s_cmp_ge_i32 s1, s17
	s_mov_b32 s0, s1
	s_cbranch_scc0 .LBB0_307
	v_readlane_b32 s70, v253, 53
	s_mov_b64 s[68:69], 0x80
	v_readlane_b32 s71, v253, 54
	s_and_b64 vcc, exec, s[12:13]
	s_cbranch_vccz .LBB0_310

; #define PG8_STAGE(bufoff, gbase, voff) do { _Pragma("unroll") for (int _i = 0; _i < 2; ++_i) \
;         __builtin_amdgcn_global_load_lds((const unsigned*)((const char*)(gbase) + (voff)[_i]), (PG8_LAS unsigned*)(lds + (bufoff) + ldsw + _i * 8192), 16, 0, 0); } while (0)
; #define PG8_LDA(dst, b, h) do { _Pragma("unroll") for (int m = 0; m < 4; ++m) _Pragma("unroll") for (int k = 0; k < 2; ++k) dst[m][k] = *(const PG8_LAS bf16x8*)(lds + PG8_SA(b, h) + aoff + m * 2048 + k * 1024); } while (0)
; #define PG8_LDB(dst, b, h) do { _Pragma("unroll") for (int n = 0; n < 2; ++n) _Pragma("unroll") for (int k = 0; k < 2; ++k) dst[n][k] = *(const PG8_LAS bf16x8*)(lds + PG8_SB(b, h) + boff + n * 2048 + k * 1024); } while (0)
; #define PG8_MMA(ai, bj, At, Bt) do { __builtin_amdgcn_s_setprio(1); _Pragma("unroll") for (int m = 0; m < 4; ++m) _Pragma("unroll") for (int n = 0; n < 2; ++n) _Pragma("unroll") for (int k = 0; k < 2; ++k) \
;         acc[ai][bj][m][n] = __builtin_amdgcn_mfma_f32_16x16x32_bf16(Bt[n][k], At[m][k], acc[ai][bj][m][n], 0, 0, 0); __builtin_amdgcn_s_setprio(0); } while (0)
; #define PG8_WAIT_V(n) asm volatile("s_waitcnt vmcnt(" #n ")" ::: "memory")
; #define PG8_BAR __builtin_amdgcn_s_barrier()
; template <class Epi, class Sched, bool ALIGN_EPI = false, bool SP2 = false>
; __device__ __forceinline__ void gemm_phase(PG8_LAS unsigned char* lds, const Gemm g, const Sched& S, const Epi& E, int tid_in) {
;     ...
;         for (int t = 0; t < nt; t += 2) {
;             const bool last = (t == nt - 2);
;             const char* a1 = cA + (size_t)(t + 1) * kstep;
;             const char* a2 = last ? nA : cA + (size_t)(t + 2) * kstep; const char* b2 = last ? nB : cB + (size_t)(t + 2) * kstep;
;             const char* a3 = a2 + kstep; const char* b3 = b2 + kstep;
;             if (last && has_next) S.a_ready(nxt);
;             if constexpr (SP2) {
;             PG8_LDB(B0, 0, 0); PG8_LDB(B1, 0, 1); PG8_SCHED; PG8_LDA(At, 0, 0); PG8_STAGE(PG8_SA(1, 1), a1 + hstep, voffA);
;             PG8_WAIT_V(8); PG8_WAIT_L(0); PG8_BAR; PG8_MMA(0, 0, At, B0); PG8_MMA(0, 1, At, B1); PG8_BAR; PG8_SCHED;
;             PG8_LDA(At, 0, 1); PG8_STAGE(PG8_SB(0, 0), b2, voffB); PG8_STAGE(PG8_SB(0, 1), b2 + hstep, voffB); PG8_STAGE(PG8_SA(0, 0), a2, voffA);
;             PG8_WAIT_V(8); PG8_WAIT_L(0); PG8_BAR; PG8_MMA(1, 0, At, B0); PG8_MMA(1, 1, At, B1); PG8_BAR; PG8_SCHED;
.LBB0_351:
	s_add_u32 s2, s20, 0xfffc0080
	s_addc_u32 s3, s21, -1
	s_add_i32 s33, 0, 0x10000
	s_cmp_eq_u32 s49, 12
	s_cselect_b32 s25, s11, s3
	s_cselect_b32 s24, s44, s2
	s_cselect_b32 s23, s9, s48
	s_cselect_b32 s22, s45, s47
	s_add_i32 s34, 0, 0x14000
	v_add_u32_e32 v60, s33, v164
	v_add_u32_e32 v174, s34, v164
	ds_read_b128 v[48:51], v60
	ds_read_b128 v[52:55], v60 offset:1024
	ds_read_b128 v[56:59], v60 offset:2048
	ds_read_b128 v[60:63], v60 offset:3072
	ds_read_b128 v[158:161], v174
	ds_read_b128 v[166:169], v174 offset:1024
	ds_read_b128 v[170:173], v174 offset:2048
	ds_read_b128 v[174:177], v174 offset:3072
	v_lshl_add_u64 v[210:211], s[20:21], 0, v[154:155]
	s_add_i32 m0, s19, 0xc000
	ds_read_b128 v[178:181], v165
	ds_read_b128 v[182:185], v165 offset:1024
	ds_read_b128 v[186:189], v165 offset:2048
	ds_read_b128 v[190:193], v165 offset:3072
	ds_read_b128 v[194:197], v165 offset:4096
	ds_read_b128 v[198:201], v165 offset:5120
	ds_read_b128 v[202:205], v165 offset:6144
	ds_read_b128 v[206:209], v165 offset:7168
	global_load_lds_dwordx4 v[210:211], off
	v_lshl_add_u64 v[210:211], s[20:21], 0, v[156:157]
	s_add_i32 m0, s19, 0xe000
	s_nop 0
	global_load_lds_dwordx4 v[210:211], off
	s_waitcnt vmcnt(8)
	s_waitcnt lgkmcnt(0)
	s_barrier
	s_setprio 1
	s_waitcnt lgkmcnt(0)
	v_mfma_f32_16x16x32_bf16 v[140:143], v[48:51], v[178:181], v[140:143]
	v_mfma_f32_16x16x32_bf16 v[136:139], v[56:59], v[178:181], v[136:139]
	v_mfma_f32_16x16x32_bf16 v[124:127], v[48:51], v[186:189], v[124:127]
	v_mfma_f32_16x16x32_bf16 v[120:123], v[56:59], v[186:189], v[120:123]
	v_mfma_f32_16x16x32_bf16 v[108:111], v[48:51], v[194:197], v[108:111]
	v_mfma_f32_16x16x32_bf16 v[104:107], v[56:59], v[194:197], v[104:107]
	v_mfma_f32_16x16x32_bf16 v[92:95], v[48:51], v[202:205], v[92:95]
	v_mfma_f32_16x16x32_bf16 v[88:91], v[56:59], v[202:205], v[88:91]
	v_mfma_f32_16x16x32_bf16 v[140:143], v[52:55], v[182:185], v[140:143]
	v_mfma_f32_16x16x32_bf16 v[136:139], v[60:63], v[182:185], v[136:139]
	v_mfma_f32_16x16x32_bf16 v[124:127], v[52:55], v[190:193], v[124:127]
	v_mfma_f32_16x16x32_bf16 v[120:123], v[60:63], v[190:193], v[120:123]
	v_mfma_f32_16x16x32_bf16 v[108:111], v[52:55], v[198:201], v[108:111]
	v_mfma_f32_16x16x32_bf16 v[104:107], v[60:63], v[198:201], v[104:107]
	v_mfma_f32_16x16x32_bf16 v[92:95], v[52:55], v[206:209], v[92:95]
	v_mfma_f32_16x16x32_bf16 v[88:91], v[60:63], v[206:209], v[88:91]
	v_mfma_f32_16x16x32_bf16 v[132:135], v[158:161], v[178:181], v[132:135]
	v_mfma_f32_16x16x32_bf16 v[128:131], v[170:173], v[178:181], v[128:131]
	v_mfma_f32_16x16x32_bf16 v[116:119], v[158:161], v[186:189], v[116:119]
	v_mfma_f32_16x16x32_bf16 v[112:115], v[170:173], v[186:189], v[112:115]
	v_mfma_f32_16x16x32_bf16 v[100:103], v[158:161], v[194:197], v[100:103]
	v_mfma_f32_16x16x32_bf16 v[96:99], v[170:173], v[194:197], v[96:99]
	v_mfma_f32_16x16x32_bf16 v[84:87], v[158:161], v[202:205], v[84:87]
	v_mfma_f32_16x16x32_bf16 v[80:83], v[170:173], v[202:205], v[80:83]
	v_mfma_f32_16x16x32_bf16 v[132:135], v[166:169], v[182:185], v[132:135]
	v_mfma_f32_16x16x32_bf16 v[128:131], v[174:177], v[182:185], v[128:131]
	v_mfma_f32_16x16x32_bf16 v[116:119], v[166:169], v[190:193], v[116:119]
	v_mfma_f32_16x16x32_bf16 v[112:115], v[174:177], v[190:193], v[112:115]
	v_mfma_f32_16x16x32_bf16 v[100:103], v[166:169], v[198:201], v[100:103]
	v_mfma_f32_16x16x32_bf16 v[96:99], v[174:177], v[198:201], v[96:99]
	v_mfma_f32_16x16x32_bf16 v[84:87], v[166:169], v[206:209], v[84:87]
	v_mfma_f32_16x16x32_bf16 v[80:83], v[174:177], v[206:209], v[80:83]
	s_setprio 0
	s_barrier
	s_add_i32 s2, s33, s35
	v_lshl_add_u64 v[210:211], s[22:23], 0, v[144:145]
	s_mov_b32 m0, s2
	ds_read_b128 v[178:181], v165 offset:16384
	ds_read_b128 v[182:185], v165 offset:17408
	ds_read_b128 v[186:189], v165 offset:18432
	ds_read_b128 v[190:193], v165 offset:19456
	ds_read_b128 v[194:197], v165 offset:20480
	ds_read_b128 v[198:201], v165 offset:21504
	ds_read_b128 v[202:205], v165 offset:22528
	ds_read_b128 v[206:209], v165 offset:23552
	global_load_lds_dwordx4 v[210:211], off
	s_add_i32 m0, s2, 0x2000
	s_add_u32 s2, s22, 0x40000
	v_lshl_add_u64 v[212:213], s[22:23], 0, v[148:149]
	s_addc_u32 s3, s23, 0
	s_add_i32 s33, s34, s35
	global_load_lds_dwordx4 v[212:213], off
	v_lshl_add_u64 v[214:215], s[2:3], 0, v[144:145]
	s_mov_b32 m0, s33
	v_lshl_add_u64 v[216:217], s[24:25], 0, v[150:151]
	global_load_lds_dwordx4 v[214:215], off
	v_lshl_add_u64 v[214:215], s[2:3], 0, v[148:149]
	s_add_i32 m0, s33, 0x2000
	s_nop 0
	global_load_lds_dwordx4 v[214:215], off
	v_lshl_add_u64 v[214:215], s[24:25], 0, v[152:153]
	s_mov_b32 m0, s19
	s_nop 0
	global_load_lds_dwordx4 v[214:215], off
	s_mov_b32 m0, s36
	s_nop 0
	global_load_lds_dwordx4 v[216:217], off
	s_waitcnt vmcnt(8)
	s_waitcnt lgkmcnt(0)
	s_barrier
; #define PG8_STAGE(bufoff, gbase, voff) do { _Pragma("unroll") for (int _i = 0; _i < 2; ++_i) \
;         __builtin_amdgcn_global_load_lds((const unsigned*)((const char*)(gbase) + (voff)[_i]), (PG8_LAS unsigned*)(lds + (bufoff) + ldsw + _i * 8192), 16, 0, 0); } while (0)
; #define PG8_LDA(dst, b, h) do { _Pragma("unroll") for (int m = 0; m < 4; ++m) _Pragma("unroll") for (int k = 0; k < 2; ++k) dst[m][k] = *(const PG8_LAS bf16x8*)(lds + PG8_SA(b, h) + aoff + m * 2048 + k * 1024); } while (0)
; #define PG8_LDB(dst, b, h) do { _Pragma("unroll") for (int n = 0; n < 2; ++n) _Pragma("unroll") for (int k = 0; k < 2; ++k) dst[n][k] = *(const PG8_LAS bf16x8*)(lds + PG8_SB(b, h) + boff + n * 2048 + k * 1024); } while (0)
; #define PG8_MMA(ai, bj, At, Bt) do { __builtin_amdgcn_s_setprio(1); _Pragma("unroll") for (int m = 0; m < 4; ++m) _Pragma("unroll") for (int n = 0; n < 2; ++n) _Pragma("unroll") for (int k = 0; k < 2; ++k) \
;         acc[ai][bj][m][n] = __builtin_amdgcn_mfma_f32_16x16x32_bf16(Bt[n][k], At[m][k], acc[ai][bj][m][n], 0, 0, 0); __builtin_amdgcn_s_setprio(0); } while (0)
; #define PG8_WAIT_V(n) asm volatile("s_waitcnt vmcnt(" #n ")" ::: "memory")
; #define PG8_WAIT_L(n) asm volatile("s_waitcnt lgkmcnt(" #n ")" ::: "memory")
; #define PG8_BAR __builtin_amdgcn_s_barrier()
; #define PG8_SCHED __builtin_amdgcn_sched_barrier(0)
; template <class Epi, class Sched, bool ALIGN_EPI = false, bool SP2 = false>
; __device__ __forceinline__ void gemm_phase(PG8_LAS unsigned char* lds, const Gemm g, const Sched& S, const Epi& E, int tid_in) {
;     ...
;             PG8_WAIT_V(8); PG8_WAIT_L(0); PG8_BAR; PG8_MMA(1, 0, At, B0); PG8_MMA(1, 1, At, B1); PG8_BAR; PG8_SCHED;
;             PG8_LDB(B0, 1, 0); PG8_LDB(B1, 1, 1); PG8_SCHED; PG8_LDA(At, 1, 0); PG8_STAGE(PG8_SA(0, 1), a2 + hstep, voffA);
;             PG8_WAIT_V(8); PG8_WAIT_L(0); PG8_BAR; PG8_MMA(0, 0, At, B0); PG8_MMA(0, 1, At, B1); PG8_BAR; PG8_SCHED;
	s_setprio 1
	s_waitcnt lgkmcnt(0)
	v_mfma_f32_16x16x32_bf16 v[76:79], v[48:51], v[178:181], v[76:79]
	v_mfma_f32_16x16x32_bf16 v[72:75], v[56:59], v[178:181], v[72:75]
	v_mfma_f32_16x16x32_bf16 v[44:47], v[48:51], v[186:189], v[44:47]
	v_mfma_f32_16x16x32_bf16 v[40:43], v[56:59], v[186:189], v[40:43]
	v_mfma_f32_16x16x32_bf16 v[28:31], v[48:51], v[194:197], v[28:31]
	v_mfma_f32_16x16x32_bf16 v[24:27], v[56:59], v[194:197], v[24:27]
	v_mfma_f32_16x16x32_bf16 v[12:15], v[48:51], v[202:205], v[12:15]
	v_mfma_f32_16x16x32_bf16 v[8:11], v[56:59], v[202:205], v[8:11]
	v_mfma_f32_16x16x32_bf16 v[76:79], v[52:55], v[182:185], v[76:79]
	v_mfma_f32_16x16x32_bf16 v[72:75], v[60:63], v[182:185], v[72:75]
	v_mfma_f32_16x16x32_bf16 v[44:47], v[52:55], v[190:193], v[44:47]
	v_mfma_f32_16x16x32_bf16 v[40:43], v[60:63], v[190:193], v[40:43]
	v_mfma_f32_16x16x32_bf16 v[28:31], v[52:55], v[198:201], v[28:31]
	v_mfma_f32_16x16x32_bf16 v[24:27], v[60:63], v[198:201], v[24:27]
	v_mfma_f32_16x16x32_bf16 v[12:15], v[52:55], v[206:209], v[12:15]
	v_mfma_f32_16x16x32_bf16 v[8:11], v[60:63], v[206:209], v[8:11]
	v_mfma_f32_16x16x32_bf16 v[36:39], v[158:161], v[186:189], v[36:39]
	v_mfma_f32_16x16x32_bf16 v[32:35], v[170:173], v[186:189], v[32:35]
	v_mfma_f32_16x16x32_bf16 v[20:23], v[158:161], v[194:197], v[20:23]
	v_mfma_f32_16x16x32_bf16 v[16:19], v[170:173], v[194:197], v[16:19]
	v_mfma_f32_16x16x32_bf16 v[4:7], v[158:161], v[202:205], v[4:7]
	v_mfma_f32_16x16x32_bf16 v[0:3], v[170:173], v[202:205], v[0:3]
	v_mfma_f32_16x16x32_bf16 v[48:51], v[158:161], v[178:181], v[68:71]
	v_mfma_f32_16x16x32_bf16 v[52:55], v[170:173], v[178:181], v[64:67]
	v_mfma_f32_16x16x32_bf16 v[36:39], v[166:169], v[190:193], v[36:39]
	v_mfma_f32_16x16x32_bf16 v[32:35], v[174:177], v[190:193], v[32:35]
	v_mfma_f32_16x16x32_bf16 v[20:23], v[166:169], v[198:201], v[20:23]
	v_mfma_f32_16x16x32_bf16 v[16:19], v[174:177], v[198:201], v[16:19]
	v_mfma_f32_16x16x32_bf16 v[4:7], v[166:169], v[206:209], v[4:7]
	v_mfma_f32_16x16x32_bf16 v[0:3], v[174:177], v[206:209], v[0:3]
	v_mfma_f32_16x16x32_bf16 v[48:51], v[166:169], v[182:185], v[48:51]
	v_mfma_f32_16x16x32_bf16 v[52:55], v[174:177], v[182:185], v[52:55]
	s_setprio 0
	s_barrier
	s_add_i32 s33, 0, 0x18000
	s_add_i32 s34, 0, 0x1c000
	v_add_u32_e32 v68, s33, v164
	v_add_u32_e32 v174, s34, v164
	ds_read_b128 v[56:59], v68
	ds_read_b128 v[60:63], v68 offset:1024
	ds_read_b128 v[64:67], v68 offset:2048
	ds_read_b128 v[68:71], v68 offset:3072
	ds_read_b128 v[158:161], v174
	ds_read_b128 v[166:169], v174 offset:1024
	ds_read_b128 v[170:173], v174 offset:2048
	ds_read_b128 v[174:177], v174 offset:3072
	s_add_u32 s2, s24, 0x40000
	s_addc_u32 s3, s25, 0
	s_mov_b32 m0, s37
	v_lshl_add_u64 v[218:219], s[2:3], 0, v[152:153]
	ds_read_b128 v[178:181], v165 offset:32768
	ds_read_b128 v[182:185], v165 offset:33792
	ds_read_b128 v[186:189], v165 offset:34816
	ds_read_b128 v[190:193], v165 offset:35840
	ds_read_b128 v[194:197], v165 offset:36864
	ds_read_b128 v[198:201], v165 offset:37888
	ds_read_b128 v[202:205], v165 offset:38912
	ds_read_b128 v[206:209], v165 offset:39936
	global_load_lds_dwordx4 v[218:219], off
	v_lshl_add_u64 v[218:219], s[2:3], 0, v[150:151]
	s_mov_b32 m0, s38
	s_nop 0
	global_load_lds_dwordx4 v[218:219], off
	s_waitcnt vmcnt(8)
	s_waitcnt lgkmcnt(0)
	s_barrier
	s_setprio 1
	s_waitcnt lgkmcnt(0)
	v_mfma_f32_16x16x32_bf16 v[140:143], v[56:59], v[178:181], v[140:143]
	v_mfma_f32_16x16x32_bf16 v[136:139], v[64:67], v[178:181], v[136:139]
	v_mfma_f32_16x16x32_bf16 v[124:127], v[56:59], v[186:189], v[124:127]
	v_mfma_f32_16x16x32_bf16 v[120:123], v[64:67], v[186:189], v[120:123]
	v_mfma_f32_16x16x32_bf16 v[108:111], v[56:59], v[194:197], v[108:111]
	v_mfma_f32_16x16x32_bf16 v[104:107], v[64:67], v[194:197], v[104:107]
	v_mfma_f32_16x16x32_bf16 v[92:95], v[56:59], v[202:205], v[92:95]
	v_mfma_f32_16x16x32_bf16 v[88:91], v[64:67], v[202:205], v[88:91]
	v_mfma_f32_16x16x32_bf16 v[140:143], v[60:63], v[182:185], v[140:143]
	v_mfma_f32_16x16x32_bf16 v[136:139], v[68:71], v[182:185], v[136:139]
	v_mfma_f32_16x16x32_bf16 v[124:127], v[60:63], v[190:193], v[124:127]
	v_mfma_f32_16x16x32_bf16 v[120:123], v[68:71], v[190:193], v[120:123]
	v_mfma_f32_16x16x32_bf16 v[108:111], v[60:63], v[198:201], v[108:111]
	v_mfma_f32_16x16x32_bf16 v[104:107], v[68:71], v[198:201], v[104:107]
	v_mfma_f32_16x16x32_bf16 v[92:95], v[60:63], v[206:209], v[92:95]
	v_mfma_f32_16x16x32_bf16 v[88:91], v[68:71], v[206:209], v[88:91]
	v_mfma_f32_16x16x32_bf16 v[132:135], v[158:161], v[178:181], v[132:135]
	v_mfma_f32_16x16x32_bf16 v[128:131], v[170:173], v[178:181], v[128:131]
	v_mfma_f32_16x16x32_bf16 v[116:119], v[158:161], v[186:189], v[116:119]
	v_mfma_f32_16x16x32_bf16 v[112:115], v[170:173], v[186:189], v[112:115]
	v_mfma_f32_16x16x32_bf16 v[100:103], v[158:161], v[194:197], v[100:103]
	v_mfma_f32_16x16x32_bf16 v[96:99], v[170:173], v[194:197], v[96:99]
	v_mfma_f32_16x16x32_bf16 v[84:87], v[158:161], v[202:205], v[84:87]
	v_mfma_f32_16x16x32_bf16 v[80:83], v[170:173], v[202:205], v[80:83]
	v_mfma_f32_16x16x32_bf16 v[132:135], v[166:169], v[182:185], v[132:135]
	v_mfma_f32_16x16x32_bf16 v[128:131], v[174:177], v[182:185], v[128:131]
	v_mfma_f32_16x16x32_bf16 v[116:119], v[166:169], v[190:193], v[116:119]
	v_mfma_f32_16x16x32_bf16 v[112:115], v[174:177], v[190:193], v[112:115]
	v_mfma_f32_16x16x32_bf16 v[100:103], v[166:169], v[198:201], v[100:103]
	v_mfma_f32_16x16x32_bf16 v[96:99], v[174:177], v[198:201], v[96:99]
	v_mfma_f32_16x16x32_bf16 v[84:87], v[166:169], v[206:209], v[84:87]
	v_mfma_f32_16x16x32_bf16 v[80:83], v[174:177], v[206:209], v[80:83]
	s_setprio 0
	s_barrier
; #define PG8_STAGE(bufoff, gbase, voff) do { _Pragma("unroll") for (int _i = 0; _i < 2; ++_i) \
;         __builtin_amdgcn_global_load_lds((const unsigned*)((const char*)(gbase) + (voff)[_i]), (PG8_LAS unsigned*)(lds + (bufoff) + ldsw + _i * 8192), 16, 0, 0); } while (0)
; #define PG8_LDA(dst, b, h) do { _Pragma("unroll") for (int m = 0; m < 4; ++m) _Pragma("unroll") for (int k = 0; k < 2; ++k) dst[m][k] = *(const PG8_LAS bf16x8*)(lds + PG8_SA(b, h) + aoff + m * 2048 + k * 1024); } while (0)
; #define PG8_MMA(ai, bj, At, Bt) do { __builtin_amdgcn_s_setprio(1); _Pragma("unroll") for (int m = 0; m < 4; ++m) _Pragma("unroll") for (int n = 0; n < 2; ++n) _Pragma("unroll") for (int k = 0; k < 2; ++k) \
;         acc[ai][bj][m][n] = __builtin_amdgcn_mfma_f32_16x16x32_bf16(Bt[n][k], At[m][k], acc[ai][bj][m][n], 0, 0, 0); __builtin_amdgcn_s_setprio(0); } while (0)
; #define PG8_WAIT_V(n) asm volatile("s_waitcnt vmcnt(" #n ")" ::: "memory")
; #define PG8_WAIT_L(n) asm volatile("s_waitcnt lgkmcnt(" #n ")" ::: "memory")
; #define PG8_BAR __builtin_amdgcn_s_barrier()
; #define PG8_SCHED __builtin_amdgcn_sched_barrier(0)
; template <class Epi, class Sched, bool ALIGN_EPI = false, bool SP2 = false>
; __device__ __forceinline__ void gemm_phase(PG8_LAS unsigned char* lds, const Gemm g, const Sched& S, const Epi& E, int tid_in) {
;     ...
;             PG8_LDA(At, 1, 1); PG8_STAGE(PG8_SB(1, 0), b3, voffB); PG8_STAGE(PG8_SB(1, 1), b3 + hstep, voffB); PG8_STAGE(PG8_SA(1, 0), a3, voffA);
;             PG8_WAIT_V(8); PG8_WAIT_L(0); PG8_BAR; PG8_MMA(1, 0, At, B0); PG8_MMA(1, 1, At, B1); PG8_BAR; PG8_SCHED;
	s_add_i32 s2, s33, s35
	v_lshl_add_u64 v[210:211], v[210:211], 0, s[68:69]
	s_mov_b32 m0, s2
	ds_read_b128 v[178:181], v165 offset:49152
	ds_read_b128 v[182:185], v165 offset:50176
	ds_read_b128 v[186:189], v165 offset:51200
	ds_read_b128 v[190:193], v165 offset:52224
	ds_read_b128 v[194:197], v165 offset:53248
	ds_read_b128 v[198:201], v165 offset:54272
	ds_read_b128 v[202:205], v165 offset:55296
	ds_read_b128 v[206:209], v165 offset:56320
	global_load_lds_dwordx4 v[210:211], off
	s_add_i32 m0, s2, 0x2000
	s_add_u32 s2, s22, 0x40080
	v_lshl_add_u64 v[210:211], v[212:213], 0, s[68:69]
	s_addc_u32 s3, s23, 0
	s_add_i32 s22, s34, s35
	global_load_lds_dwordx4 v[210:211], off
	v_lshl_add_u64 v[210:211], s[2:3], 0, v[144:145]
	s_mov_b32 m0, s22
	s_nop 0
	global_load_lds_dwordx4 v[210:211], off
	v_lshl_add_u64 v[210:211], s[2:3], 0, v[148:149]
	s_add_i32 m0, s22, 0x2000
	s_nop 0
	global_load_lds_dwordx4 v[210:211], off
	v_lshl_add_u64 v[210:211], v[214:215], 0, s[68:69]
	s_mov_b32 m0, s41
	s_nop 0
	global_load_lds_dwordx4 v[210:211], off
	v_lshl_add_u64 v[210:211], v[216:217], 0, s[68:69]
	s_mov_b32 m0, s42
	s_nop 0
	global_load_lds_dwordx4 v[210:211], off
	s_waitcnt vmcnt(8)
	s_waitcnt lgkmcnt(0)
	s_barrier
	s_setprio 1
	s_waitcnt lgkmcnt(0)
	v_mfma_f32_16x16x32_bf16 v[76:79], v[56:59], v[178:181], v[76:79]
	v_mfma_f32_16x16x32_bf16 v[72:75], v[64:67], v[178:181], v[72:75]
	v_mfma_f32_16x16x32_bf16 v[44:47], v[56:59], v[186:189], v[44:47]
	v_mfma_f32_16x16x32_bf16 v[40:43], v[64:67], v[186:189], v[40:43]
	v_mfma_f32_16x16x32_bf16 v[28:31], v[56:59], v[194:197], v[28:31]
	v_mfma_f32_16x16x32_bf16 v[24:27], v[64:67], v[194:197], v[24:27]
	v_mfma_f32_16x16x32_bf16 v[12:15], v[56:59], v[202:205], v[12:15]
	v_mfma_f32_16x16x32_bf16 v[8:11], v[64:67], v[202:205], v[8:11]
	v_mfma_f32_16x16x32_bf16 v[76:79], v[60:63], v[182:185], v[76:79]
	v_mfma_f32_16x16x32_bf16 v[72:75], v[68:71], v[182:185], v[72:75]
	v_mfma_f32_16x16x32_bf16 v[44:47], v[60:63], v[190:193], v[44:47]
	v_mfma_f32_16x16x32_bf16 v[40:43], v[68:71], v[190:193], v[40:43]
	v_mfma_f32_16x16x32_bf16 v[28:31], v[60:63], v[198:201], v[28:31]
	v_mfma_f32_16x16x32_bf16 v[24:27], v[68:71], v[198:201], v[24:27]
	v_mfma_f32_16x16x32_bf16 v[12:15], v[60:63], v[206:209], v[12:15]
	v_mfma_f32_16x16x32_bf16 v[8:11], v[68:71], v[206:209], v[8:11]
	v_mfma_f32_16x16x32_bf16 v[48:51], v[158:161], v[178:181], v[48:51]
	v_mfma_f32_16x16x32_bf16 v[68:71], v[166:169], v[182:185], v[48:51]
	v_mfma_f32_16x16x32_bf16 v[48:51], v[170:173], v[178:181], v[52:55]
	v_mfma_f32_16x16x32_bf16 v[36:39], v[158:161], v[186:189], v[36:39]
	v_mfma_f32_16x16x32_bf16 v[32:35], v[170:173], v[186:189], v[32:35]
	v_mfma_f32_16x16x32_bf16 v[20:23], v[158:161], v[194:197], v[20:23]
	v_mfma_f32_16x16x32_bf16 v[16:19], v[170:173], v[194:197], v[16:19]
	v_mfma_f32_16x16x32_bf16 v[4:7], v[158:161], v[202:205], v[4:7]
	v_mfma_f32_16x16x32_bf16 v[0:3], v[170:173], v[202:205], v[0:3]
	v_mfma_f32_16x16x32_bf16 v[64:67], v[174:177], v[182:185], v[48:51]
	v_mfma_f32_16x16x32_bf16 v[36:39], v[166:169], v[190:193], v[36:39]
	v_mfma_f32_16x16x32_bf16 v[32:35], v[174:177], v[190:193], v[32:35]
	v_mfma_f32_16x16x32_bf16 v[20:23], v[166:169], v[198:201], v[20:23]
	v_mfma_f32_16x16x32_bf16 v[16:19], v[174:177], v[198:201], v[16:19]
	v_mfma_f32_16x16x32_bf16 v[4:7], v[166:169], v[206:209], v[4:7]
	v_mfma_f32_16x16x32_bf16 v[0:3], v[174:177], v[206:209], v[0:3]
	s_setprio 0
	s_barrier
	s_add_i32 s49, s49, 2
	s_add_u32 s20, s20, 0x100
	s_addc_u32 s21, s21, 0
	s_add_u32 s47, s47, 0x100
	s_addc_u32 s48, s48, 0
	s_cmp_gt_u32 s49, 13
	s_cbranch_scc0 .LBB0_351
	s_and_b64 vcc, exec, s[6:7]
	s_cbranch_vccz .LBB0_354
	s_barrier
